# scan v4: output waves stage their own q rows through private LDS two chunks ahead; loader fetches qk and u two chunks ahead
# speedup vs baseline: 1.0173x; 1.0173x over previous
; #define TIDX opaque_tid()
; DEVI void scan_item(const Params& p, int h, int sl, char* smem) {
;   const int tid = TIDX, lane = tid & 63, wave = tid >> 6, l15 = lane & 15, quad = lane >> 4;
;   bf16_t* r1 = (bf16_t*)(p.ws + OFF_R1);
;   const bf16_t* r0 = (const bf16_t*)(p.ws + OFF_R0);
;   char* wsm = smem;
;   char* qksm = smem + 17408;
;   char* ktsm = smem + 26624;
;   char* usm = smem + 45056;
;   float* gsm = (float*)(smem + 50176);
;   char* sbx = smem + 51200;
;   char* vbx = smem + 59392;
;   constexpr int USTR = (NW * 16 + 8) * 2;
;   const int vb0 = sl * NW * 16;
;   const bool is_state = wave < NW;
;   const int cw = is_state ? wave : wave - NW;
;   u32x4 pw[4], pqk[2], pkt[4], pg = u32x4{0, 0, 0, 0}, pu = u32x4{0, 0, 0, 0};
;     ...
;   bf16x8 qfr[2][4];
;   auto qload = [&](int n) {
;     const int t0 = n * 64 - 48;
; #pragma unroll
;     for (int mt = 0; mt < 2; ++mt) {
;       const int t = t0 + (cw * 2 + mt) * 16 + l15;
; #pragma unroll
;       for (int s = 0; s < 4; ++s) {
;         u32x4 v4 = u32x4{0, 0, 0, 0};
;         if (t >= 0) v4 = *(const u32x4*)(r1 + (size_t)t * 3072 + h * 128 + s * 32 + quad * 8);
;         qfr[mt][s] = __builtin_bit_cast(bf16x8, v4);
;       }
;     }
;   };
.LBB0_1158:
	s_and_b64 vcc, exec, s[0:1]
	s_cbranch_vccz .LBB0_1238
	v_lshrrev_b32_e32 v2, 6, v206
	v_and_b32_e32 v0, 63, v206
	v_readfirstlane_b32 s5, v2
	s_and_b32 s9, s88, 7
	s_lshr_b32 s13, s88, 3
	v_and_b32_e32 v3, 15, v0
	v_lshrrev_b32_e32 v4, 4, v0
	s_lshl_b32 s18, s9, 8
	s_add_u32 s0, s14, 0x9bab000
	s_addc_u32 s1, s15, 0
	s_add_u32 s0, s0, s18
	s_addc_u32 s1, s1, 0
	s_cmp_eq_u32 s5, 0
	s_cbranch_scc1 .Lsc_state
	s_cmp_eq_u32 s5, 3
	s_cbranch_scc1 .Lsc_loader
	s_sub_u32 s24, s5, 1
	s_mul_i32 s37, s24, 0x2000
	s_lshl_b32 s24, s24, 1
	s_lshl_b32 s25, s24, 4
	v_add_u32_e32 v5, s25, v3
	v_mul_u32_u24_e32 v6, 0x1800, v5
	v_lshlrev_b32_e32 v104, 2, v5
	v_add_u32_e32 v104, 0x1800, v104
	s_lshl_b32 s36, s13, 5
	v_lshl_add_u32 v7, v4, 3, s36
	v_add_u32_e32 v7, 0x1000, v7
	v_add_u32_e32 v106, v6, v7
	v_add_u32_e32 v6, 0, v3
	v_lshlrev_b32_e32 v6, 8, v6
	v_add_u32_e32 v6, s37, v6
	v_or_b32_e32 v7, 0, v4
	v_xor_b32_e32 v7, v7, v3
	v_lshl_add_u32 v116, v7, 4, v6
	v_add_u32_e32 v116, 12320, v116
	v_or_b32_e32 v7, 4, v4
	v_xor_b32_e32 v7, v7, v3
	v_lshl_add_u32 v117, v7, 4, v6
	v_add_u32_e32 v117, 12320, v117
	v_or_b32_e32 v7, 8, v4
	v_xor_b32_e32 v7, v7, v3
	v_lshl_add_u32 v118, v7, 4, v6
	v_add_u32_e32 v118, 12320, v118
	v_or_b32_e32 v7, 12, v4
	v_xor_b32_e32 v7, v7, v3
	v_lshl_add_u32 v119, v7, 4, v6
	v_add_u32_e32 v119, 12320, v119
	v_lshlrev_b32_e32 v6, 7, v5
	v_and_b32_e32 v2, 7, v3
	v_or_b32_e32 v7, 0, v4
	v_xor_b32_e32 v7, v7, v2
	v_lshl_add_u32 v124, v7, 4, v6
	v_add_u32_e32 v124, 28704, v124
	v_or_b32_e32 v7, 4, v4
	v_xor_b32_e32 v7, v7, v2
	v_lshl_add_u32 v125, v7, 4, v6
	v_add_u32_e32 v125, 28704, v125
	v_add_u32_e32 v5, s25, v3
	v_add_u32_e32 v5, 16, v5
	v_mul_u32_u24_e32 v6, 0x1800, v5
	v_lshlrev_b32_e32 v105, 2, v5
	v_add_u32_e32 v105, 0x1800, v105
	s_lshl_b32 s36, s13, 5
	v_lshl_add_u32 v7, v4, 3, s36
	v_add_u32_e32 v7, 0x1000, v7
	v_add_u32_e32 v107, v6, v7
	v_add_u32_e32 v6, 16, v3
	v_lshlrev_b32_e32 v6, 8, v6
	v_add_u32_e32 v6, s37, v6
	v_or_b32_e32 v7, 0, v4
	v_xor_b32_e32 v7, v7, v3
	v_lshl_add_u32 v120, v7, 4, v6
	v_add_u32_e32 v120, 12320, v120
	v_or_b32_e32 v7, 4, v4
	v_xor_b32_e32 v7, v7, v3
	v_lshl_add_u32 v121, v7, 4, v6
	v_add_u32_e32 v121, 12320, v121
	v_or_b32_e32 v7, 8, v4
	v_xor_b32_e32 v7, v7, v3
	v_lshl_add_u32 v122, v7, 4, v6
	v_add_u32_e32 v122, 12320, v122
	v_or_b32_e32 v7, 12, v4
	v_xor_b32_e32 v7, v7, v3
	v_lshl_add_u32 v123, v7, 4, v6
	v_add_u32_e32 v123, 12320, v123
	v_lshlrev_b32_e32 v6, 7, v5
	v_and_b32_e32 v2, 7, v3
	v_or_b32_e32 v7, 0, v4
	v_xor_b32_e32 v7, v7, v2
	v_lshl_add_u32 v126, v7, 4, v6
	v_add_u32_e32 v126, 28704, v126
	v_or_b32_e32 v7, 4, v4
	v_xor_b32_e32 v7, v7, v2
	v_lshl_add_u32 v127, v7, 4, v6
	v_add_u32_e32 v127, 28704, v127
	v_lshlrev_b32_e32 v108, 4, v0
	v_add_u32_e32 v108, 32, v108
	v_add_u32_e32 v5, s25, v4
	v_mul_u32_u24_e32 v5, 0x1800, v5
	v_lshl_add_u32 v5, v3, 4, v5
	v_add_u32_e32 v5, 0xc0000, v5
	v_mov_b32_e32 v198, v5
	v_add_u32_e32 v199, 0x6000, v5
	v_add_u32_e32 v200, 0xc000, v5
	v_add_u32_e32 v201, 0x12000, v5
	v_add_u32_e32 v202, 0x18000, v5
	v_add_u32_e32 v203, 0x1e000, v5
	v_add_u32_e32 v204, 0x24000, v5
	v_add_u32_e32 v205, 0x2a000, v5
	v_add_u32_e32 v6, 0, v4
	v_xor_b32_e32 v7, v6, v3
	v_lshlrev_b32_e32 v6, 8, v6
	v_lshl_add_u32 v226, v7, 4, v6
	v_add_u32_e32 v226, s37, v226
	v_add_u32_e32 v226, 12320, v226
	v_add_u32_e32 v6, 4, v4
	v_xor_b32_e32 v7, v6, v3
	v_lshlrev_b32_e32 v6, 8, v6
	v_lshl_add_u32 v227, v7, 4, v6
	v_add_u32_e32 v227, s37, v227
	v_add_u32_e32 v227, 12320, v227
	v_add_u32_e32 v6, 8, v4
	v_xor_b32_e32 v7, v6, v3
	v_lshlrev_b32_e32 v6, 8, v6
	v_lshl_add_u32 v228, v7, 4, v6
	v_add_u32_e32 v228, s37, v228
	v_add_u32_e32 v228, 12320, v228
	v_add_u32_e32 v6, 12, v4
	v_xor_b32_e32 v7, v6, v3
	v_lshlrev_b32_e32 v6, 8, v6
	v_lshl_add_u32 v229, v7, 4, v6
	v_add_u32_e32 v229, s37, v229
	v_add_u32_e32 v229, 12320, v229
	s_mul_i32 s18, s9, 0x300
	s_add_u32 s10, s14, 0x6bc1800
	s_addc_u32 s11, s15, 0
	s_add_u32 s10, s10, s18
	s_addc_u32 s11, s11, 0
	global_load_dword v56, v104, s[10:11]
	global_load_dword v57, v105, s[10:11]
	s_sub_u32 s38, s0, 0x60000
	s_subb_u32 s39, s1, 0
	global_load_dwordx4 v[128:131], v198, s[38:39]
	global_load_dwordx4 v[132:135], v199, s[38:39]
	global_load_dwordx4 v[136:139], v200, s[38:39]
	global_load_dwordx4 v[140:143], v201, s[38:39]
	global_load_dwordx4 v[144:147], v202, s[38:39]
	global_load_dwordx4 v[148:151], v203, s[38:39]
	global_load_dwordx4 v[152:155], v204, s[38:39]
	global_load_dwordx4 v[156:159], v205, s[38:39]
	global_load_dwordx4 v[160:163], v198, s[0:1]
	global_load_dwordx4 v[164:167], v199, s[0:1]
	global_load_dwordx4 v[168:171], v200, s[0:1]
	global_load_dwordx4 v[172:175], v201, s[0:1]
	global_load_dwordx4 v[176:179], v202, s[0:1]
	global_load_dwordx4 v[180:183], v203, s[0:1]
	global_load_dwordx4 v[190:193], v204, s[0:1]
	global_load_dwordx4 v[194:197], v205, s[0:1]
	s_mov_b32 s18, 0
	s_waitcnt vmcnt(0)
	s_barrier
; DEVI bf16_t f2bf(float a) { return (bf16_t)(pack2(a, 0.f) & 0xffff); }
; #define MFMA16(a, b, c) __builtin_amdgcn_mfma_f32_16x16x32_bf16((a), (b), (c), 0, 0, 0)
; DEVI void scan_item(const Params& p, int h, int sl, char* smem) {
;     ...
;   for (int n = 0; n < NCH; ++n) {
;     lstore();
;     if (is_state) {
; #pragma unroll
;       for (int s = 0; s < 4; ++s) *(bf16x8*)(sbx + ((cw * 4 + s) * 64 + lane) * 16) = pack8(S[2 * s], S[2 * s + 1]);
;     }
;     __syncthreads();
;     ...
;       f32x4 acco[2][NW];
; #pragma unroll
;       for (int ct = 0; ct < NW; ++ct) {
;         bf16x8 sb[4];
; #pragma unroll
;         for (int s = 0; s < 4; ++s) sb[s] = *(const bf16x8*)(sbx + ((ct * 4 + s) * 64 + lane) * 16);
; #pragma unroll
;         for (int m = 0; m < 2; ++m) acco[m][ct] = f32x4{0.f, 0.f, 0.f, 0.f};
; #pragma unroll
;         for (int s = 0; s < 4; ++s)
; #pragma unroll
;           for (int m = 0; m < 2; ++m) acco[m][ct] = MFMA16(qfr[m][s], sb[s], acco[m][ct]);
;       }
;       if (n + 1 < NCH) qload(n + 1);
;       __syncthreads();
;       const int t0 = n * 64 - 48;
; #pragma unroll
;       for (int m = 0; m < 2; ++m) {
;         const int mt = cw * 2 + m;
;         bf16x8 qkf[2];
; #pragma unroll
;         for (int s2 = 0; s2 < 2; ++s2) {
;           const char* a = qksm + (mt * 16 + l15) * 144 + s2 * 64 + quad * 8;
;           qkf[s2] = mk8(*(const u32x2*)a, *(const u32x2*)(a + 32));
;         }
;         const f32x4 ge4 = *(const f32x4*)(gsm + mt * 16 + quad * 4);
; #pragma unroll
;         for (int ct = 0; ct < NW; ++ct) {
;           f32x4 a2 = f32x4{0.f, 0.f, 0.f, 0.f};
; #pragma unroll
;           for (int s2 = 0; s2 < 2; ++s2) {
;             const bf16x8 vb = *(const bf16x8*)(vbx + ((ct * 2 + s2) * 64 + lane) * 16);
;             a2 = MFMA16(qkf[s2], vb, a2);
;           }
; #pragma unroll
;           for (int jj = 0; jj < 4; ++jj) {
;             const int t = t0 + mt * 16 + quad * 4 + jj;
;             const float o = ge4[jj] * acco[m][ct][jj] + a2[jj];
;             if (t >= 0) r1[(size_t)t * 3072 + 2048 + h * 128 + vb0 + ct * 16 + l15] = f2bf(o);
;           }
;         }
.Lsc_out_loop:
	s_bitcmp1_b32 s18, 0
	s_cbranch_scc1 .Lsc_out_odd
	s_add_u32 s0, s0, 0x60000
	s_addc_u32 s1, s1, 0
	s_add_u32 s10, s10, 0x1800
	s_addc_u32 s11, s11, 0
	s_barrier
	s_waitcnt vmcnt(16)
	ds_write_b128 v226, v[128:131] offset:0
	ds_write_b128 v227, v[132:135] offset:0
	ds_write_b128 v228, v[136:139] offset:0
	ds_write_b128 v229, v[140:143] offset:0
	ds_write_b128 v226, v[144:147] offset:4096
	ds_write_b128 v227, v[148:151] offset:4096
	ds_write_b128 v228, v[152:155] offset:4096
	ds_write_b128 v229, v[156:159] offset:4096
	s_cmp_ge_u32 s18, 255
	s_cbranch_scc1 .Lsc_out_noq0
	global_load_dwordx4 v[128:131], v198, s[0:1]
	global_load_dwordx4 v[132:135], v199, s[0:1]
	global_load_dwordx4 v[136:139], v200, s[0:1]
	global_load_dwordx4 v[140:143], v201, s[0:1]
	global_load_dwordx4 v[144:147], v202, s[0:1]
	global_load_dwordx4 v[148:151], v203, s[0:1]
	global_load_dwordx4 v[152:155], v204, s[0:1]
	global_load_dwordx4 v[156:159], v205, s[0:1]
.Lsc_out_noq0:
	ds_read_b128 v[60:63], v108 offset:0
	ds_read_b128 v[64:67], v108 offset:1024
	ds_read_b128 v[68:71], v108 offset:2048
	ds_read_b128 v[72:75], v108 offset:3072
	s_waitcnt lgkmcnt(4)
	ds_read_b128 v[8:11], v116
	ds_read_b128 v[12:15], v117
	ds_read_b128 v[16:19], v118
	ds_read_b128 v[20:23], v119
	ds_read_b128 v[24:27], v120
	ds_read_b128 v[28:31], v121
	ds_read_b128 v[32:35], v122
	ds_read_b128 v[36:39], v123
	ds_read_b128 v[76:79], v108 offset:4096
	ds_read_b128 v[80:83], v108 offset:5120
	s_waitcnt lgkmcnt(9)
	v_mfma_f32_16x16x32_bf16 v[84:87], v[60:63], v[8:11], 0
	s_waitcnt lgkmcnt(8)
	v_mfma_f32_16x16x32_bf16 v[84:87], v[64:67], v[12:15], v[84:87]
	s_waitcnt lgkmcnt(7)
	v_mfma_f32_16x16x32_bf16 v[84:87], v[68:71], v[16:19], v[84:87]
	s_waitcnt lgkmcnt(6)
	v_mfma_f32_16x16x32_bf16 v[84:87], v[72:75], v[20:23], v[84:87]
	s_waitcnt lgkmcnt(5)
	v_mfma_f32_16x16x32_bf16 v[88:91], v[60:63], v[24:27], 0
	s_waitcnt lgkmcnt(4)
	v_mfma_f32_16x16x32_bf16 v[88:91], v[64:67], v[28:31], v[88:91]
	s_waitcnt lgkmcnt(3)
	v_mfma_f32_16x16x32_bf16 v[88:91], v[68:71], v[32:35], v[88:91]
	s_waitcnt lgkmcnt(2)
	v_mfma_f32_16x16x32_bf16 v[88:91], v[72:75], v[36:39], v[88:91]
	ds_read_b128 v[40:43], v124 offset:0
	ds_read_b128 v[44:47], v125 offset:0
	ds_read_b128 v[48:51], v126 offset:0
	ds_read_b128 v[52:55], v127 offset:0
	s_waitcnt lgkmcnt(3)
	v_mfma_f32_16x16x32_bf16 v[92:95], v[76:79], v[40:43], 0
	s_waitcnt lgkmcnt(2)
	v_mfma_f32_16x16x32_bf16 v[92:95], v[80:83], v[44:47], v[92:95]
	s_waitcnt lgkmcnt(1)
	v_mfma_f32_16x16x32_bf16 v[96:99], v[76:79], v[48:51], 0
	s_waitcnt lgkmcnt(0)
	v_mfma_f32_16x16x32_bf16 v[96:99], v[80:83], v[52:55], v[96:99]
	s_lshl_b32 s36, s18, 2
	s_add_u32 s36, s36, s24
	s_waitcnt vmcnt(11)
	s_nop 4
	v_fma_f32 v110, -v56, v84, v92
	v_fma_f32 v111, -v56, v85, v93
	v_fma_f32 v112, -v56, v86, v94
	v_fma_f32 v113, -v56, v87, v95
	global_load_dword v56, v104, s[10:11]
	v_cvt_pk_bf16_f32 v114, v110, v111
	v_cvt_pk_bf16_f32 v115, v112, v113
	s_cmp_lt_u32 s36, 3
	s_cbranch_scc1 .Lsc_out_skip0_0
	global_store_dwordx2 v106, v[114:115], s[0:1]
.Lsc_out_skip0_0:
	s_waitcnt vmcnt(11)
	v_fma_f32 v110, -v57, v88, v96
	v_fma_f32 v111, -v57, v89, v97
	v_fma_f32 v112, -v57, v90, v98
	v_fma_f32 v113, -v57, v91, v99
	global_load_dword v57, v105, s[10:11]
	v_cvt_pk_bf16_f32 v114, v110, v111
	v_cvt_pk_bf16_f32 v115, v112, v113
	s_cmp_lt_u32 s36, 2
	s_cbranch_scc1 .Lsc_out_skip1_0
	global_store_dwordx2 v107, v[114:115], s[0:1]

; DEVI bf16_t f2bf(float a) { return (bf16_t)(pack2(a, 0.f) & 0xffff); }
; #define MFMA16(a, b, c) __builtin_amdgcn_mfma_f32_16x16x32_bf16((a), (b), (c), 0, 0, 0)
; DEVI void scan_item(const Params& p, int h, int sl, char* smem) {
;     ...
;   for (int n = 0; n < NCH; ++n) {
;     lstore();
;     if (is_state) {
; #pragma unroll
;       for (int s = 0; s < 4; ++s) *(bf16x8*)(sbx + ((cw * 4 + s) * 64 + lane) * 16) = pack8(S[2 * s], S[2 * s + 1]);
;     }
;     __syncthreads();
;     ...
;       f32x4 acco[2][NW];
; #pragma unroll
;       for (int ct = 0; ct < NW; ++ct) {
;         bf16x8 sb[4];
; #pragma unroll
;         for (int s = 0; s < 4; ++s) sb[s] = *(const bf16x8*)(sbx + ((ct * 4 + s) * 64 + lane) * 16);
; #pragma unroll
;         for (int m = 0; m < 2; ++m) acco[m][ct] = f32x4{0.f, 0.f, 0.f, 0.f};
; #pragma unroll
;         for (int s = 0; s < 4; ++s)
; #pragma unroll
;           for (int m = 0; m < 2; ++m) acco[m][ct] = MFMA16(qfr[m][s], sb[s], acco[m][ct]);
;       }
;       if (n + 1 < NCH) qload(n + 1);
;       __syncthreads();
;       const int t0 = n * 64 - 48;
; #pragma unroll
;       for (int m = 0; m < 2; ++m) {
;         const int mt = cw * 2 + m;
;         bf16x8 qkf[2];
; #pragma unroll
;         for (int s2 = 0; s2 < 2; ++s2) {
;           const char* a = qksm + (mt * 16 + l15) * 144 + s2 * 64 + quad * 8;
;           qkf[s2] = mk8(*(const u32x2*)a, *(const u32x2*)(a + 32));
;         }
;         const f32x4 ge4 = *(const f32x4*)(gsm + mt * 16 + quad * 4);
; #pragma unroll
;         for (int ct = 0; ct < NW; ++ct) {
;           f32x4 a2 = f32x4{0.f, 0.f, 0.f, 0.f};
; #pragma unroll
;           for (int s2 = 0; s2 < 2; ++s2) {
;             const bf16x8 vb = *(const bf16x8*)(vbx + ((ct * 2 + s2) * 64 + lane) * 16);
;             a2 = MFMA16(qkf[s2], vb, a2);
;           }
; #pragma unroll
;           for (int jj = 0; jj < 4; ++jj) {
;             const int t = t0 + mt * 16 + quad * 4 + jj;
;             const float o = ge4[jj] * acco[m][ct][jj] + a2[jj];
;             if (t >= 0) r1[(size_t)t * 3072 + 2048 + h * 128 + vb0 + ct * 16 + l15] = f2bf(o);
;           }
;         }
.Lsc_out_odd:
	s_add_u32 s0, s0, 0x60000
	s_addc_u32 s1, s1, 0
	s_add_u32 s10, s10, 0x1800
	s_addc_u32 s11, s11, 0
	s_barrier
	s_waitcnt vmcnt(16)
	ds_write_b128 v226, v[160:163] offset:0
	ds_write_b128 v227, v[164:167] offset:0
	ds_write_b128 v228, v[168:171] offset:0
	ds_write_b128 v229, v[172:175] offset:0
	ds_write_b128 v226, v[176:179] offset:4096
	ds_write_b128 v227, v[180:183] offset:4096
	ds_write_b128 v228, v[190:193] offset:4096
	ds_write_b128 v229, v[194:197] offset:4096
	s_cmp_ge_u32 s18, 255
	s_cbranch_scc1 .Lsc_out_noq1
	global_load_dwordx4 v[160:163], v198, s[0:1]
	global_load_dwordx4 v[164:167], v199, s[0:1]
	global_load_dwordx4 v[168:171], v200, s[0:1]
	global_load_dwordx4 v[172:175], v201, s[0:1]
	global_load_dwordx4 v[176:179], v202, s[0:1]
	global_load_dwordx4 v[180:183], v203, s[0:1]
	global_load_dwordx4 v[190:193], v204, s[0:1]
	global_load_dwordx4 v[194:197], v205, s[0:1]
.Lsc_out_noq1:
	ds_read_b128 v[60:63], v108 offset:6144
	ds_read_b128 v[64:67], v108 offset:7168
	ds_read_b128 v[68:71], v108 offset:8192
	ds_read_b128 v[72:75], v108 offset:9216
	s_waitcnt lgkmcnt(4)
	ds_read_b128 v[8:11], v116
	ds_read_b128 v[12:15], v117
	ds_read_b128 v[16:19], v118
	ds_read_b128 v[20:23], v119
	ds_read_b128 v[24:27], v120
	ds_read_b128 v[28:31], v121
	ds_read_b128 v[32:35], v122
	ds_read_b128 v[36:39], v123
	ds_read_b128 v[76:79], v108 offset:10240
	ds_read_b128 v[80:83], v108 offset:11264
	s_waitcnt lgkmcnt(9)
	v_mfma_f32_16x16x32_bf16 v[84:87], v[60:63], v[8:11], 0
	s_waitcnt lgkmcnt(8)
	v_mfma_f32_16x16x32_bf16 v[84:87], v[64:67], v[12:15], v[84:87]
	s_waitcnt lgkmcnt(7)
	v_mfma_f32_16x16x32_bf16 v[84:87], v[68:71], v[16:19], v[84:87]
	s_waitcnt lgkmcnt(6)
	v_mfma_f32_16x16x32_bf16 v[84:87], v[72:75], v[20:23], v[84:87]
	s_waitcnt lgkmcnt(5)
	v_mfma_f32_16x16x32_bf16 v[88:91], v[60:63], v[24:27], 0
	s_waitcnt lgkmcnt(4)
	v_mfma_f32_16x16x32_bf16 v[88:91], v[64:67], v[28:31], v[88:91]
	s_waitcnt lgkmcnt(3)
	v_mfma_f32_16x16x32_bf16 v[88:91], v[68:71], v[32:35], v[88:91]
	s_waitcnt lgkmcnt(2)
	v_mfma_f32_16x16x32_bf16 v[88:91], v[72:75], v[36:39], v[88:91]
	ds_read_b128 v[40:43], v124 offset:8192
	ds_read_b128 v[44:47], v125 offset:8192
	ds_read_b128 v[48:51], v126 offset:8192
	ds_read_b128 v[52:55], v127 offset:8192
	s_waitcnt lgkmcnt(3)
	v_mfma_f32_16x16x32_bf16 v[92:95], v[76:79], v[40:43], 0
	s_waitcnt lgkmcnt(2)
	v_mfma_f32_16x16x32_bf16 v[92:95], v[80:83], v[44:47], v[92:95]
	s_waitcnt lgkmcnt(1)
	v_mfma_f32_16x16x32_bf16 v[96:99], v[76:79], v[48:51], 0
	s_waitcnt lgkmcnt(0)
	v_mfma_f32_16x16x32_bf16 v[96:99], v[80:83], v[52:55], v[96:99]
	s_lshl_b32 s36, s18, 2
	s_add_u32 s36, s36, s24
	s_waitcnt vmcnt(11)
	s_nop 4
	v_fma_f32 v110, -v56, v84, v92
	v_fma_f32 v111, -v56, v85, v93
	v_fma_f32 v112, -v56, v86, v94
	v_fma_f32 v113, -v56, v87, v95
	global_load_dword v56, v104, s[10:11]
	v_cvt_pk_bf16_f32 v114, v110, v111
	v_cvt_pk_bf16_f32 v115, v112, v113
	s_cmp_lt_u32 s36, 3
	s_cbranch_scc1 .Lsc_out_skip0_1
	global_store_dwordx2 v106, v[114:115], s[0:1]

; DEVI void scan_item(const Params& p, int h, int sl, char* smem) {
;     ...
;   auto gload = [&](int n) {
;     const int t0 = n * 64 - 48;
; #pragma unroll
;     for (int i = 0; i < 4; ++i) {
;       const int ch = tid + i * 256, row = ch >> 4, kc = ch & 15;
;       const int t = t0 + row;
;       pw[i] = u32x4{0, 0, 0, 0};
;       if (t >= 0) pw[i] = *(const u32x4*)(r1 + (size_t)t * 3072 + 1024 + h * 128 + kc * 8);
;     }
;     const bf16_t* qk = r0 + R0_QK + (size_t)(n * 8 + h) * 4096;
; #pragma unroll
;     for (int i = 0; i < 2; ++i) pqk[i] = *(const u32x4*)(qk + (size_t)(tid + i * 256) * 8);
;     const bf16_t* kt = r0 + R0_KT + (size_t)(n * 8 + h) * 8192;
; #pragma unroll
;     for (int i = 0; i < 4; ++i) pkt[i] = *(const u32x4*)(kt + (size_t)(tid + i * 256) * 8);
;     if (tid < 48) pg = *(const u32x4*)((const float*)(r0 + R0_G) + (size_t)(n * 8 + h) * 192 + tid * 4);
;     if (tid < 64 * NW * 2) {
;       const int row = tid / (NW * 2), kc = tid % (NW * 2);
;       const int t = t0 + row;
;       pu = u32x4{0, 0, 0, 0};
;       if (t >= 0) pu = *(const u32x4*)(r1 + (size_t)t * 3072 + 2048 + h * 128 + vb0 + kc * 8);
;     }
;   };
;   auto lstore = [&]() {
; #pragma unroll
;     for (int i = 0; i < 4; ++i) {
;       const int ch = tid + i * 256, row = ch >> 4, kc = ch & 15;
;       *(u32x4*)(wsm + row * 272 + kc * 16) = pw[i];
;     }
;     if (tid < 48) *(u32x4*)(gsm + tid * 4) = pg;
;     if (tid < 64 * NW * 2) {
;       const int row = tid / (NW * 2), kc = tid % (NW * 2);
;       *(u32x4*)(usm + row * USTR + kc * 16) = pu;
;     }
;   };
;   auto lstore2 = [&]() {
; #pragma unroll
;     for (int i = 0; i < 2; ++i) {
;       const int ch = tid + i * 256, row = ch >> 3, kc = ch & 7;
;       *(u32x4*)(qksm + row * 144 + kc * 16) = pqk[i];
;     }
; #pragma unroll
;     for (int i = 0; i < 4; ++i) {
;       const int ch = tid + i * 256, row = ch >> 3, kc = ch & 7;
;       *(u32x4*)(ktsm + row * 144 + kc * 16) = pkt[i];
;     }
;   };
.Lsc_out_skip1_1:
.Lsc_out_join:
	s_cmp_eq_u32 s18, 0
	s_cbranch_scc1 .Lsc_out_drain
	s_cmp_lt_u32 s18, 254
	s_cbranch_scc1 .Lsc_out_nodrain
.Lsc_out_drain:
	s_waitcnt vmcnt(0)
.Lsc_out_nodrain:
	s_add_u32 s18, s18, 1
	s_cmp_lt_u32 s18, 257
	s_cbranch_scc1 .Lsc_out_loop
	s_branch .Lsc_done
.Lsc_loader:
	s_lshl_b32 s40, s13, 5
	v_lshl_add_u32 v5, v3, 1, s40
	v_mul_u32_u24_e32 v6, 0x6000, v4
	v_add_u32_e32 v5, v5, v6
	v_add_u32_e32 v5, 0x121000, v5
	v_mov_b32_e32 v120, v5
	v_add_u32_e32 v121, 0x1800, v5
	v_add_u32_e32 v122, 0x3000, v5
	v_add_u32_e32 v123, 0x4800, v5
	v_lshlrev_b32_e32 v128, 4, v0
	v_add_u32_e32 v128, 0x20000, v128
	v_lshrrev_b32_e32 v5, 3, v0
	v_and_b32_e32 v6, 7, v0
	v_xor_b32_e32 v6, v6, v5
	v_lshlrev_b32_e32 v5, 7, v5
	v_lshl_add_u32 v134, v6, 4, v5
	v_add_u32_e32 v134, 28704, v134
	v_lshlrev_b32_e32 v129, 4, v0
	v_add_u32_e32 v129, 45088, v129
	s_add_u32 s6, s0, 0x18000
	s_addc_u32 s7, s1, 0
	s_add_u32 s10, s0, 0x30000
	s_addc_u32 s11, s1, 0
	s_add_u32 s16, s0, 0x48000
	s_addc_u32 s17, s1, 0
	s_lshl_b32 s40, s9, 13
	s_add_u32 s24, s14, 0x5ba4000
	s_addc_u32 s25, s15, 0
	s_add_u32 s24, s24, s40
	s_addc_u32 s25, s25, 0
	s_sub_u32 s36, s0, 0xc0000
	s_subb_u32 s37, s1, 0
	s_sub_u32 s38, s6, 0xc0000
	s_subb_u32 s39, s7, 0
	s_sub_u32 s40, s10, 0xc0000
	s_subb_u32 s41, s11, 0
	s_sub_u32 s42, s16, 0xc0000
	s_subb_u32 s43, s17, 0
	global_load_ushort v24, v120, s[36:37]
	global_load_ushort v25, v121, s[36:37]
	global_load_ushort v26, v122, s[36:37]
	global_load_ushort v27, v123, s[36:37]
	global_load_ushort v28, v120, s[38:39]
	global_load_ushort v29, v121, s[38:39]
	global_load_ushort v30, v122, s[38:39]
	global_load_ushort v31, v123, s[38:39]
	global_load_ushort v32, v120, s[40:41]
	global_load_ushort v33, v121, s[40:41]
	global_load_ushort v34, v122, s[40:41]
	global_load_ushort v35, v123, s[40:41]
	global_load_ushort v36, v120, s[42:43]
	global_load_ushort v37, v121, s[42:43]
	global_load_ushort v38, v122, s[42:43]
	global_load_ushort v39, v123, s[42:43]
	s_waitcnt vmcnt(0)
	v_mov_b32_e32 v24, 0
	v_mov_b32_e32 v25, 0
	v_mov_b32_e32 v26, 0
	v_mov_b32_e32 v27, 0
	v_mov_b32_e32 v28, 0
	v_mov_b32_e32 v29, 0
	v_mov_b32_e32 v30, 0
	v_mov_b32_e32 v31, 0
	v_mov_b32_e32 v32, 0
	v_mov_b32_e32 v33, 0
	v_mov_b32_e32 v34, 0
	v_mov_b32_e32 v35, 0
	v_lshlrev_b32_e32 v24, 16, v24
	v_lshlrev_b32_e32 v25, 16, v25
	v_lshlrev_b32_e32 v26, 16, v26
	v_lshlrev_b32_e32 v27, 16, v27
	v_lshlrev_b32_e32 v28, 16, v28
	v_lshlrev_b32_e32 v29, 16, v29
	v_lshlrev_b32_e32 v30, 16, v30
	v_lshlrev_b32_e32 v31, 16, v31
	v_lshlrev_b32_e32 v32, 16, v32
	v_lshlrev_b32_e32 v33, 16, v33
	v_lshlrev_b32_e32 v34, 16, v34
	v_lshlrev_b32_e32 v35, 16, v35
	v_lshlrev_b32_e32 v36, 16, v36
	v_lshlrev_b32_e32 v37, 16, v37
	v_lshlrev_b32_e32 v38, 16, v38
	v_lshlrev_b32_e32 v39, 16, v39
	ds_write_b128 v129, v[24:27] offset:0
	ds_write_b128 v129, v[28:31] offset:1024
	ds_write_b128 v129, v[32:35] offset:2048
	ds_write_b128 v129, v[36:39] offset:3072
	s_sub_u32 s44, s24, 0x10000
	s_subb_u32 s45, s25, 0
	global_load_dwordx4 v[40:43], v128, s[44:45] offset:-4096
	global_load_dwordx4 v[44:47], v128, s[44:45] offset:-3072
	global_load_dwordx4 v[48:51], v128, s[44:45] offset:-2048
	global_load_dwordx4 v[52:55], v128, s[44:45] offset:-1024
	global_load_dwordx4 v[56:59], v128, s[44:45] offset:0
	global_load_dwordx4 v[60:63], v128, s[44:45] offset:1024
	global_load_dwordx4 v[64:67], v128, s[44:45] offset:2048
	global_load_dwordx4 v[68:71], v128, s[44:45] offset:3072
	s_sub_u32 s36, s0, 0x60000
	s_subb_u32 s37, s1, 0
	s_sub_u32 s38, s6, 0x60000
	s_subb_u32 s39, s7, 0
	s_sub_u32 s40, s10, 0x60000
	s_subb_u32 s41, s11, 0
	s_sub_u32 s42, s16, 0x60000
	s_subb_u32 s43, s17, 0
	global_load_ushort v8, v120, s[36:37]
	global_load_ushort v9, v121, s[36:37]
	global_load_ushort v10, v122, s[36:37]
	global_load_ushort v11, v123, s[36:37]
	global_load_ushort v12, v120, s[38:39]
	global_load_ushort v13, v121, s[38:39]
	global_load_ushort v14, v122, s[38:39]
	global_load_ushort v15, v123, s[38:39]
	global_load_ushort v16, v120, s[40:41]
	global_load_ushort v17, v121, s[40:41]
	global_load_ushort v18, v122, s[40:41]
	global_load_ushort v19, v123, s[40:41]
	global_load_ushort v20, v120, s[42:43]
	global_load_ushort v21, v121, s[42:43]
	global_load_ushort v22, v122, s[42:43]
	global_load_ushort v23, v123, s[42:43]
	s_add_u32 s44, s44, 0x10000
	s_addc_u32 s45, s45, 0
	global_load_dwordx4 v[72:75], v128, s[44:45] offset:-4096
	global_load_dwordx4 v[76:79], v128, s[44:45] offset:-3072
	global_load_dwordx4 v[80:83], v128, s[44:45] offset:-2048
	global_load_dwordx4 v[84:87], v128, s[44:45] offset:-1024
	global_load_dwordx4 v[88:91], v128, s[44:45] offset:0
	global_load_dwordx4 v[92:95], v128, s[44:45] offset:1024
	global_load_dwordx4 v[96:99], v128, s[44:45] offset:2048
	global_load_dwordx4 v[100:103], v128, s[44:45] offset:3072
	global_load_ushort v24, v120, s[0:1]
	global_load_ushort v25, v121, s[0:1]
	global_load_ushort v26, v122, s[0:1]
	global_load_ushort v27, v123, s[0:1]
	global_load_ushort v28, v120, s[6:7]
	global_load_ushort v29, v121, s[6:7]
	global_load_ushort v30, v122, s[6:7]
	global_load_ushort v31, v123, s[6:7]
	global_load_ushort v32, v120, s[10:11]
	global_load_ushort v33, v121, s[10:11]
	global_load_ushort v34, v122, s[10:11]
	global_load_ushort v35, v123, s[10:11]
	global_load_ushort v36, v120, s[16:17]
	global_load_ushort v37, v121, s[16:17]
	global_load_ushort v38, v122, s[16:17]
	global_load_ushort v39, v123, s[16:17]
	s_waitcnt lgkmcnt(0)
	s_barrier
	s_mov_b32 s18, 0
; DEVI void scan_item(const Params& p, int h, int sl, char* smem) {
;     ...
;   auto gload = [&](int n) {
;     const int t0 = n * 64 - 48;
; #pragma unroll
;     for (int i = 0; i < 4; ++i) {
;       const int ch = tid + i * 256, row = ch >> 4, kc = ch & 15;
;       const int t = t0 + row;
;       pw[i] = u32x4{0, 0, 0, 0};
;       if (t >= 0) pw[i] = *(const u32x4*)(r1 + (size_t)t * 3072 + 1024 + h * 128 + kc * 8);
;     }
;     const bf16_t* qk = r0 + R0_QK + (size_t)(n * 8 + h) * 4096;
; #pragma unroll
;     for (int i = 0; i < 2; ++i) pqk[i] = *(const u32x4*)(qk + (size_t)(tid + i * 256) * 8);
;     const bf16_t* kt = r0 + R0_KT + (size_t)(n * 8 + h) * 8192;
; #pragma unroll
;     for (int i = 0; i < 4; ++i) pkt[i] = *(const u32x4*)(kt + (size_t)(tid + i * 256) * 8);
;     if (tid < 48) pg = *(const u32x4*)((const float*)(r0 + R0_G) + (size_t)(n * 8 + h) * 192 + tid * 4);
;     if (tid < 64 * NW * 2) {
;       const int row = tid / (NW * 2), kc = tid % (NW * 2);
;       const int t = t0 + row;
;       pu = u32x4{0, 0, 0, 0};
;       if (t >= 0) pu = *(const u32x4*)(r1 + (size_t)t * 3072 + 2048 + h * 128 + vb0 + kc * 8);
;     }
;   };
;   auto lstore = [&]() {
; #pragma unroll
;     for (int i = 0; i < 4; ++i) {
;       const int ch = tid + i * 256, row = ch >> 4, kc = ch & 15;
;       *(u32x4*)(wsm + row * 272 + kc * 16) = pw[i];
;     }
;     if (tid < 48) *(u32x4*)(gsm + tid * 4) = pg;
;     if (tid < 64 * NW * 2) {
;       const int row = tid / (NW * 2), kc = tid % (NW * 2);
;       *(u32x4*)(usm + row * USTR + kc * 16) = pu;
;     }
;   };
;   auto lstore2 = [&]() {
; #pragma unroll
;     for (int i = 0; i < 2; ++i) {
;       const int ch = tid + i * 256, row = ch >> 3, kc = ch & 7;
;       *(u32x4*)(qksm + row * 144 + kc * 16) = pqk[i];
;     }
; #pragma unroll
;     for (int i = 0; i < 4; ++i) {
;       const int ch = tid + i * 256, row = ch >> 3, kc = ch & 7;
;       *(u32x4*)(ktsm + row * 144 + kc * 16) = pkt[i];
;     }
;   };
.Lsc_ld_loop:
	s_bitcmp1_b32 s18, 0
	s_cbranch_scc1 .Lsc_ld_odd
	s_cmp_ge_u32 s18, 255
	s_cbranch_scc0 .Lsc_ld_cw0
	s_waitcnt vmcnt(0)
.Lsc_ld_cw0:
	s_waitcnt vmcnt(40)
	ds_write_b128 v134, v[40:43] offset:0
	ds_write_b128 v134, v[44:47] offset:1024
	ds_write_b128 v134, v[48:51] offset:2048
	ds_write_b128 v134, v[52:55] offset:3072
	ds_write_b128 v134, v[56:59] offset:4096
	ds_write_b128 v134, v[60:63] offset:5120
	ds_write_b128 v134, v[64:67] offset:6144
	ds_write_b128 v134, v[68:71] offset:7168
	s_waitcnt vmcnt(24)
	v_lshlrev_b32_e32 v8, 16, v8
	v_lshlrev_b32_e32 v9, 16, v9
	v_lshlrev_b32_e32 v10, 16, v10
	v_lshlrev_b32_e32 v11, 16, v11
	v_lshlrev_b32_e32 v12, 16, v12
	v_lshlrev_b32_e32 v13, 16, v13
	v_lshlrev_b32_e32 v14, 16, v14
	v_lshlrev_b32_e32 v15, 16, v15
	v_lshlrev_b32_e32 v16, 16, v16
	v_lshlrev_b32_e32 v17, 16, v17
	v_lshlrev_b32_e32 v18, 16, v18
	v_lshlrev_b32_e32 v19, 16, v19
	v_lshlrev_b32_e32 v20, 16, v20
	v_lshlrev_b32_e32 v21, 16, v21
	v_lshlrev_b32_e32 v22, 16, v22
	v_lshlrev_b32_e32 v23, 16, v23
	ds_write_b128 v129, v[8:11] offset:4096
	ds_write_b128 v129, v[12:15] offset:5120
	ds_write_b128 v129, v[16:19] offset:6144
	ds_write_b128 v129, v[20:23] offset:7168
	s_add_u32 s0, s0, 0x60000
	s_addc_u32 s1, s1, 0
	s_add_u32 s6, s6, 0x60000
	s_addc_u32 s7, s7, 0
	s_add_u32 s10, s10, 0x60000
	s_addc_u32 s11, s11, 0
	s_add_u32 s16, s16, 0x60000
	s_addc_u32 s17, s17, 0
	s_add_u32 s24, s24, 0x10000
	s_addc_u32 s25, s25, 0
	s_cmp_ge_u32 s18, 255
	s_cbranch_scc1 .Lsc_ld_noload0
	global_load_dwordx4 v[40:43], v128, s[24:25] offset:-4096
	global_load_dwordx4 v[44:47], v128, s[24:25] offset:-3072
	global_load_dwordx4 v[48:51], v128, s[24:25] offset:-2048
	global_load_dwordx4 v[52:55], v128, s[24:25] offset:-1024
	global_load_dwordx4 v[56:59], v128, s[24:25] offset:0
	global_load_dwordx4 v[60:63], v128, s[24:25] offset:1024
	global_load_dwordx4 v[64:67], v128, s[24:25] offset:2048
	global_load_dwordx4 v[68:71], v128, s[24:25] offset:3072
	global_load_ushort v8, v120, s[0:1]
	global_load_ushort v9, v121, s[0:1]
	global_load_ushort v10, v122, s[0:1]
	global_load_ushort v11, v123, s[0:1]
	global_load_ushort v12, v120, s[6:7]
	global_load_ushort v13, v121, s[6:7]
	global_load_ushort v14, v122, s[6:7]
	global_load_ushort v15, v123, s[6:7]
	global_load_ushort v16, v120, s[10:11]
	global_load_ushort v17, v121, s[10:11]
	global_load_ushort v18, v122, s[10:11]
	global_load_ushort v19, v123, s[10:11]
	global_load_ushort v20, v120, s[16:17]
	global_load_ushort v21, v121, s[16:17]
	global_load_ushort v22, v122, s[16:17]
	global_load_ushort v23, v123, s[16:17]

; DEVI void scan_item(const Params& p, int h, int sl, char* smem) {
;     ...
;   auto gload = [&](int n) {
;     const int t0 = n * 64 - 48;
; #pragma unroll
;     for (int i = 0; i < 4; ++i) {
;       const int ch = tid + i * 256, row = ch >> 4, kc = ch & 15;
;       const int t = t0 + row;
;       pw[i] = u32x4{0, 0, 0, 0};
;       if (t >= 0) pw[i] = *(const u32x4*)(r1 + (size_t)t * 3072 + 1024 + h * 128 + kc * 8);
;     }
;     const bf16_t* qk = r0 + R0_QK + (size_t)(n * 8 + h) * 4096;
; #pragma unroll
;     for (int i = 0; i < 2; ++i) pqk[i] = *(const u32x4*)(qk + (size_t)(tid + i * 256) * 8);
;     const bf16_t* kt = r0 + R0_KT + (size_t)(n * 8 + h) * 8192;
; #pragma unroll
;     for (int i = 0; i < 4; ++i) pkt[i] = *(const u32x4*)(kt + (size_t)(tid + i * 256) * 8);
;     if (tid < 48) pg = *(const u32x4*)((const float*)(r0 + R0_G) + (size_t)(n * 8 + h) * 192 + tid * 4);
;     if (tid < 64 * NW * 2) {
;       const int row = tid / (NW * 2), kc = tid % (NW * 2);
;       const int t = t0 + row;
;       pu = u32x4{0, 0, 0, 0};
;       if (t >= 0) pu = *(const u32x4*)(r1 + (size_t)t * 3072 + 2048 + h * 128 + vb0 + kc * 8);
;     }
;   };
;   auto lstore = [&]() {
; #pragma unroll
;     for (int i = 0; i < 4; ++i) {
;       const int ch = tid + i * 256, row = ch >> 4, kc = ch & 15;
;       *(u32x4*)(wsm + row * 272 + kc * 16) = pw[i];
;     }
;     if (tid < 48) *(u32x4*)(gsm + tid * 4) = pg;
;     if (tid < 64 * NW * 2) {
;       const int row = tid / (NW * 2), kc = tid % (NW * 2);
;       *(u32x4*)(usm + row * USTR + kc * 16) = pu;
;     }
;   };
;   auto lstore2 = [&]() {
; #pragma unroll
;     for (int i = 0; i < 2; ++i) {
;       const int ch = tid + i * 256, row = ch >> 3, kc = ch & 7;
;       *(u32x4*)(qksm + row * 144 + kc * 16) = pqk[i];
;     }
; #pragma unroll
;     for (int i = 0; i < 4; ++i) {
;       const int ch = tid + i * 256, row = ch >> 3, kc = ch & 7;
;       *(u32x4*)(ktsm + row * 144 + kc * 16) = pkt[i];
;     }
;   };
.Lsc_ld_odd:
	s_cmp_ge_u32 s18, 255
	s_cbranch_scc0 .Lsc_ld_cw1
	s_waitcnt vmcnt(0)
.Lsc_ld_cw1:
	s_waitcnt vmcnt(40)
	ds_write_b128 v134, v[72:75] offset:8192
	ds_write_b128 v134, v[76:79] offset:9216
	ds_write_b128 v134, v[80:83] offset:10240
	ds_write_b128 v134, v[84:87] offset:11264
	ds_write_b128 v134, v[88:91] offset:12288
	ds_write_b128 v134, v[92:95] offset:13312
	ds_write_b128 v134, v[96:99] offset:14336
	ds_write_b128 v134, v[100:103] offset:15360
	s_waitcnt vmcnt(24)
	v_lshlrev_b32_e32 v24, 16, v24
	v_lshlrev_b32_e32 v25, 16, v25
	v_lshlrev_b32_e32 v26, 16, v26
	v_lshlrev_b32_e32 v27, 16, v27
	v_lshlrev_b32_e32 v28, 16, v28
	v_lshlrev_b32_e32 v29, 16, v29
	v_lshlrev_b32_e32 v30, 16, v30
	v_lshlrev_b32_e32 v31, 16, v31
	v_lshlrev_b32_e32 v32, 16, v32
	v_lshlrev_b32_e32 v33, 16, v33
	v_lshlrev_b32_e32 v34, 16, v34
	v_lshlrev_b32_e32 v35, 16, v35
	v_lshlrev_b32_e32 v36, 16, v36
	v_lshlrev_b32_e32 v37, 16, v37
	v_lshlrev_b32_e32 v38, 16, v38
	v_lshlrev_b32_e32 v39, 16, v39
	ds_write_b128 v129, v[24:27] offset:0
	ds_write_b128 v129, v[28:31] offset:1024
	ds_write_b128 v129, v[32:35] offset:2048
	ds_write_b128 v129, v[36:39] offset:3072
	s_add_u32 s0, s0, 0x60000
	s_addc_u32 s1, s1, 0
	s_add_u32 s6, s6, 0x60000
	s_addc_u32 s7, s7, 0
	s_add_u32 s10, s10, 0x60000
	s_addc_u32 s11, s11, 0
	s_add_u32 s16, s16, 0x60000
	s_addc_u32 s17, s17, 0
	s_add_u32 s24, s24, 0x10000
	s_addc_u32 s25, s25, 0
	s_cmp_ge_u32 s18, 255
	s_cbranch_scc1 .Lsc_ld_noload1
	global_load_dwordx4 v[72:75], v128, s[24:25] offset:-4096
	global_load_dwordx4 v[76:79], v128, s[24:25] offset:-3072
	global_load_dwordx4 v[80:83], v128, s[24:25] offset:-2048
	global_load_dwordx4 v[84:87], v128, s[24:25] offset:-1024
	global_load_dwordx4 v[88:91], v128, s[24:25] offset:0
	global_load_dwordx4 v[92:95], v128, s[24:25] offset:1024
	global_load_dwordx4 v[96:99], v128, s[24:25] offset:2048
	global_load_dwordx4 v[100:103], v128, s[24:25] offset:3072
	global_load_ushort v24, v120, s[0:1]
	global_load_ushort v25, v121, s[0:1]
	global_load_ushort v26, v122, s[0:1]
	global_load_ushort v27, v123, s[0:1]
	global_load_ushort v28, v120, s[6:7]
	global_load_ushort v29, v121, s[6:7]
	global_load_ushort v30, v122, s[6:7]
	global_load_ushort v31, v123, s[6:7]
	global_load_ushort v32, v120, s[10:11]
	global_load_ushort v33, v121, s[10:11]
	global_load_ushort v34, v122, s[10:11]
	global_load_ushort v35, v123, s[10:11]
	global_load_ushort v36, v120, s[16:17]
	global_load_ushort v37, v121, s[16:17]
	global_load_ushort v38, v122, s[16:17]
	global_load_ushort v39, v123, s[16:17]

; DEVI void scan_item(const Params& p, int h, int sl, char* smem) {
;     ...
;   auto gload = [&](int n) {
;     const int t0 = n * 64 - 48;
; #pragma unroll
;     for (int i = 0; i < 4; ++i) {
;       const int ch = tid + i * 256, row = ch >> 4, kc = ch & 15;
;       const int t = t0 + row;
;       pw[i] = u32x4{0, 0, 0, 0};
;       if (t >= 0) pw[i] = *(const u32x4*)(r1 + (size_t)t * 3072 + 1024 + h * 128 + kc * 8);
;     }
;     const bf16_t* qk = r0 + R0_QK + (size_t)(n * 8 + h) * 4096;
; #pragma unroll
;     for (int i = 0; i < 2; ++i) pqk[i] = *(const u32x4*)(qk + (size_t)(tid + i * 256) * 8);
;     const bf16_t* kt = r0 + R0_KT + (size_t)(n * 8 + h) * 8192;
; #pragma unroll
;     for (int i = 0; i < 4; ++i) pkt[i] = *(const u32x4*)(kt + (size_t)(tid + i * 256) * 8);
;     if (tid < 48) pg = *(const u32x4*)((const float*)(r0 + R0_G) + (size_t)(n * 8 + h) * 192 + tid * 4);
;     if (tid < 64 * NW * 2) {
;       const int row = tid / (NW * 2), kc = tid % (NW * 2);
;       const int t = t0 + row;
;       pu = u32x4{0, 0, 0, 0};
;       if (t >= 0) pu = *(const u32x4*)(r1 + (size_t)t * 3072 + 2048 + h * 128 + vb0 + kc * 8);
;     }
;   };
;     ...
;   f32x4 S[8];
; #pragma unroll
;   for (int r = 0; r < 8; ++r) S[r] = f32x4{0.f, 0.f, 0.f, 0.f};
;   gload(0);
;   if (!is_state) qload(0);
.Lsc_state:
	s_setprio 3
	v_mul_u32_u24_e32 v5, 0x1800, v4
	v_lshl_add_u32 v5, v3, 4, v5
	v_add_u32_e32 v5, 0x60800, v5
	v_mov_b32_e32 v178, v5
	v_add_u32_e32 v179, 0x6000, v5
	v_add_u32_e32 v180, 0xc000, v5
	v_add_u32_e32 v181, 0x12000, v5
	v_lshlrev_b32_e32 v182, 4, v0
	v_add_u32_e32 v182, 0x20000, v182
	v_lshlrev_b32_e32 v183, 4, v4
	v_add_u32_e32 v183, 0x1900, v183
	v_lshlrev_b32_e32 v184, 4, v0
	v_add_u32_e32 v185, 45088, v184
	v_add_u32_e32 v184, 32, v184
	s_add_u32 s6, s0, 0x18000
	s_addc_u32 s7, s1, 0
	s_add_u32 s10, s0, 0x30000
	s_addc_u32 s11, s1, 0
	s_add_u32 s16, s0, 0x48000
	s_addc_u32 s17, s1, 0
	s_lshl_b32 s18, s9, 14
	s_add_u32 s24, s14, 0x3b74000
	s_addc_u32 s25, s15, 0
	s_add_u32 s24, s24, s18
	s_addc_u32 s25, s25, 0
	s_add_u32 s36, s24, 0x2000
	s_addc_u32 s37, s25, 0
	s_mul_i32 s18, s9, 0x300
	s_add_u32 s38, s14, 0x6bc1800
	s_addc_u32 s39, s15, 0
	s_add_u32 s38, s38, s18
	s_addc_u32 s39, s39, 0
	v_mov_b32_e32 v2, 0
	v_mov_b32_e32 v3, 0
	v_mov_b32_e32 v4, 0
	v_mov_b32_e32 v5, 0
	v_mov_b32_e32 v6, 0
	v_mov_b32_e32 v7, 0
	v_mov_b32_e32 v8, 0
	v_mov_b32_e32 v9, 0
	v_mov_b32_e32 v10, 0
	v_mov_b32_e32 v11, 0
	v_mov_b32_e32 v12, 0
	v_mov_b32_e32 v13, 0
	v_mov_b32_e32 v14, 0
	v_mov_b32_e32 v15, 0
	v_mov_b32_e32 v16, 0
	v_mov_b32_e32 v17, 0
	v_mov_b32_e32 v18, 0
	v_mov_b32_e32 v19, 0
	v_mov_b32_e32 v20, 0
	v_mov_b32_e32 v21, 0
	v_mov_b32_e32 v22, 0
	v_mov_b32_e32 v23, 0
	v_mov_b32_e32 v24, 0
	v_mov_b32_e32 v25, 0
	v_mov_b32_e32 v26, 0
	v_mov_b32_e32 v27, 0
	v_mov_b32_e32 v28, 0
	v_mov_b32_e32 v29, 0
	v_mov_b32_e32 v30, 0
	v_mov_b32_e32 v31, 0
	v_mov_b32_e32 v32, 0
	v_mov_b32_e32 v33, 0
	global_load_dwordx4 v[98:101], v182, s[24:25] offset:-4096
	global_load_dwordx4 v[102:105], v182, s[24:25] offset:-3072
	global_load_dwordx4 v[106:109], v182, s[24:25] offset:-2048
	global_load_dwordx4 v[110:113], v182, s[24:25] offset:-1024
	global_load_dwordx4 v[114:117], v182, s[24:25] offset:0
	global_load_dwordx4 v[118:121], v182, s[24:25] offset:1024
	global_load_dwordx4 v[122:125], v182, s[24:25] offset:2048
	global_load_dwordx4 v[126:129], v182, s[24:25] offset:3072
	global_load_dwordx4 v[130:133], v182, s[36:37] offset:-4096
	global_load_dwordx4 v[134:137], v182, s[36:37] offset:-3072
	global_load_dwordx4 v[138:141], v182, s[36:37] offset:-2048
	global_load_dwordx4 v[142:145], v182, s[36:37] offset:-1024
	global_load_dwordx4 v[146:149], v182, s[36:37] offset:0
	global_load_dwordx4 v[150:153], v182, s[36:37] offset:1024
	global_load_dwordx4 v[154:157], v182, s[36:37] offset:2048
	global_load_dwordx4 v[158:161], v182, s[36:37] offset:3072
	global_load_dwordx4 v[226:229], v183, s[38:39] offset:0
	global_load_dwordx4 v[230:233], v183, s[38:39] offset:64
	global_load_dwordx4 v[234:237], v183, s[38:39] offset:128
	global_load_dwordx4 v[238:241], v183, s[38:39] offset:192
	s_load_dword s62, s[38:39], 0x1a00
	v_mov_b32_e32 v34, 0
	v_mov_b32_e32 v35, 0
	v_mov_b32_e32 v36, 0
	v_mov_b32_e32 v37, 0
	v_mov_b32_e32 v38, 0
	v_mov_b32_e32 v39, 0
	v_mov_b32_e32 v40, 0
	v_mov_b32_e32 v41, 0
	v_mov_b32_e32 v42, 0
	v_mov_b32_e32 v43, 0
	v_mov_b32_e32 v44, 0
	v_mov_b32_e32 v45, 0
	v_mov_b32_e32 v46, 0
	v_mov_b32_e32 v47, 0
	v_mov_b32_e32 v48, 0
	v_mov_b32_e32 v49, 0
	v_mov_b32_e32 v50, 0
	v_mov_b32_e32 v51, 0
	v_mov_b32_e32 v52, 0
	v_mov_b32_e32 v53, 0
	v_mov_b32_e32 v54, 0
	v_mov_b32_e32 v55, 0
	v_mov_b32_e32 v56, 0
	v_mov_b32_e32 v57, 0
	v_mov_b32_e32 v58, 0
	v_mov_b32_e32 v59, 0
	v_mov_b32_e32 v60, 0
	v_mov_b32_e32 v61, 0
	v_mov_b32_e32 v62, 0
	v_mov_b32_e32 v63, 0
	v_mov_b32_e32 v64, 0
	v_mov_b32_e32 v65, 0
	v_mov_b32_e32 v66, 0
	v_mov_b32_e32 v67, 0
	v_mov_b32_e32 v68, 0
	v_mov_b32_e32 v69, 0
	v_mov_b32_e32 v70, 0
	v_mov_b32_e32 v71, 0
	v_mov_b32_e32 v72, 0
	v_mov_b32_e32 v73, 0
	v_mov_b32_e32 v74, 0
	v_mov_b32_e32 v75, 0
	v_mov_b32_e32 v76, 0
	v_mov_b32_e32 v77, 0
	v_mov_b32_e32 v78, 0
	v_mov_b32_e32 v79, 0
	v_mov_b32_e32 v80, 0
	v_mov_b32_e32 v81, 0
	v_mov_b32_e32 v82, 0
	v_mov_b32_e32 v83, 0
	v_mov_b32_e32 v84, 0
	v_mov_b32_e32 v85, 0
	v_mov_b32_e32 v86, 0
	v_mov_b32_e32 v87, 0
	v_mov_b32_e32 v88, 0
	v_mov_b32_e32 v89, 0
	v_mov_b32_e32 v90, 0
	v_mov_b32_e32 v91, 0
	v_mov_b32_e32 v92, 0
	v_mov_b32_e32 v93, 0
	v_mov_b32_e32 v94, 0
	v_mov_b32_e32 v95, 0
	v_mov_b32_e32 v96, 0
	v_mov_b32_e32 v97, 0
	s_waitcnt vmcnt(0) lgkmcnt(0)
	s_barrier
	ds_read_b128 v[190:193], v185 offset:0
	ds_read_b128 v[194:197], v185 offset:1024
	ds_read_b128 v[198:201], v185 offset:2048
	ds_read_b128 v[202:205], v185 offset:3072
	s_mov_b32 s18, 0
